# input-projection GEMM: per-tile row scales (XS) and column scales (CS) are DMA-staged into spare LDS at tile start by two waves; the epilogue reads them with ds_read and no longer drains vmcnt(0), so
# baseline (speedup 1.0000x reference)
; #define PG8_BAR __builtin_amdgcn_s_barrier()
;     int tid_ = threadIdx.x; asm volatile("" : "+v"(tid_));
;     const int tid = tid_, wid = __builtin_amdgcn_readfirstlane(tid >> 6), lane = tid & 63, wr = wid >> 2, wc = wid & 3, fr = lane & 15, fq = lane >> 4;
;     const int K = g.K, nt = K / BK;
;     unsigned voffA[2], voffB[2];
; #pragma unroll
;     for (int i = 0; i < 2; ++i) { int R, C; stage_rc(tid * 16 + i * 8192, R, C); const int Rb = Epi::PERM ? ((R & ~31) + perm32(R & 31)) : R;
;         voffA[i] = (unsigned)(R * g.lda + C) * 2u; voffB[i] = (unsigned)(Rb * K + C) * 2u; }
;     const size_t kstep = (size_t)(BK * 2);
;     const size_t hstepA = (size_t)HALF * g.lda * 2, hstepB = (size_t)HALF * K * 2;
;     const size_t tstepA = 2 * hstepA, tstepB = 2 * hstepB;
;     const unsigned ldsw = (unsigned)wid * 1024u;
;     const int aoff = lds_byte(wr * 64 + fr, fq * 8), boff = lds_byte(wc * 32 + fr, fq * 8);
;     ...
;     Unit cur, nxt; int ui = 0;
;     if (!S.next(0, cur)) return;
;     f32x4 acc[2][2][4][2];
; #pragma unroll
;     for (int a = 0; a < 2; ++a)
; #pragma unroll
;         for (int b = 0; b < 2; ++b)
; #pragma unroll
;             for (int m = 0; m < 4; ++m)
; #pragma unroll
;                 for (int n = 0; n < 2; ++n) acc[a][b][m][n] = (f32x4){0.f, 0.f, 0.f, 0.f};
;     bf16x8 At[4][2], B0[2][2], B1[2][2];
;     const char* cA = (const char*)g.A + (size_t)cur.pm * tstepA; const char* cB = (const char*)g.Bt + (size_t)cur.pn * tstepB;
;     S.a_ready(cur);
;     if constexpr (SP2) {
;         PG8_STAGE(PG8_SB(0, 0), cB, voffB); PG8_STAGE(PG8_SB(0, 1), cB + hstepB, voffB); PG8_STAGE(PG8_SA(0, 0), cA, voffA); PG8_STAGE(PG8_SA(0, 1), cA + hstepA, voffA);
;         if (wr == 1) PG8_BAR;
;         PG8_WAIT_V(2); PG8_BAR;
;         PG8_STAGE(PG8_SB(1, 0), cB + kstep, voffB); PG8_STAGE(PG8_SA(1, 0), cA + kstep, voffA); PG8_STAGE(PG8_SB(1, 1), cB + hstepB + kstep, voffB);
;         PG8_WAIT_V(6); PG8_BAR;
;     } else {
;         PG8_STAGE(PG8_SB(0, 0), cB, voffB); PG8_STAGE(PG8_SA(0, 0), cA, voffA); PG8_STAGE(PG8_SB(0, 1), cB + hstepB, voffB); PG8_STAGE(PG8_SA(0, 1), cA + hstepA, voffA);
;         if (wr == 1) PG8_BAR;
;         PG8_WAIT_V(4); PG8_BAR;
;         PG8_STAGE(PG8_SB(1, 0), cB + kstep, voffB); PG8_STAGE(PG8_SA(1, 0), cA + kstep, voffA); PG8_STAGE(PG8_SB(1, 1), cB + hstepB + kstep, voffB);
;         PG8_WAIT_V(6); PG8_BAR;
.LBB0_319:
	s_mov_b32 s101, 0
	s_bitcmp0_b32 s20, 0
	s_cselect_b64 s[2:3], -1, 0
	v_writelane_b32 v255, s2, 13
	v_readlane_b32 s36, v252, 1
	v_readlane_b32 s49, v252, 14
	v_writelane_b32 v255, s3, 14
	s_and_b64 s[2:3], s[2:3], exec
	v_readlane_b32 s51, v252, 16
	s_mov_b64 s[0:1], 0x1ed00000
	v_readlane_b32 s48, v252, 13
	v_readlane_b32 s50, v252, 15
	s_cselect_b32 s2, s51, s49
	v_writelane_b32 v255, s2, 15
	s_cselect_b32 s2, s50, s48
	v_readlane_b32 s10, v253, 54
	s_mov_b64 s[0:1], 0
	v_writelane_b32 v255, s2, 16
	s_mov_b64 s[2:3], 0x6c00000
	s_mov_b64 s[12:13], 0xec00000
	s_mov_b64 s[4:5], 0x12c00000
	s_mov_b64 s[6:7], 0x16c00000
	s_mov_b64 s[8:9], 0x1ac00000
	v_mov_b32_e32 v5, v232
	v_readlane_b32 s11, v253, 55
	s_andn2_b64 vcc, exec, s[10:11]
	v_readfirstlane_b32 s10, v5
	v_readlane_b32 s37, v252, 2
	v_readlane_b32 s38, v252, 3
	v_readlane_b32 s39, v252, 4
	v_readlane_b32 s40, v252, 5
	v_readlane_b32 s41, v252, 6
	v_readlane_b32 s42, v252, 7
	v_readlane_b32 s43, v252, 8
	v_readlane_b32 s44, v252, 9
	v_readlane_b32 s45, v252, 10
	v_readlane_b32 s46, v252, 11
	v_readlane_b32 s47, v252, 12
	s_cbranch_vccnz .LBB0_399
	v_lshlrev_b32_e32 v0, 4, v5
	v_add_u32_e32 v1, 0x2000, v0
	v_ashrrev_i32_e32 v2, 31, v1
	v_lshrrev_b32_e32 v2, 22, v2
	v_add_u32_e32 v2, v1, v2
	v_ashrrev_i32_e32 v4, 10, v2
	v_mul_i32_i24_e32 v2, 0x400, v4
	v_sub_u32_e32 v1, v1, v2
	v_lshrrev_b32_e32 v2, 4, v1
	v_bitop3_b32 v1, v2, v1, 32 bitop3:0x6c
	v_ashrrev_i32_e32 v2, 31, v1
	v_lshrrev_b32_e32 v2, 26, v2
	v_add_u32_e32 v2, v1, v2
	v_lshlrev_b32_e32 v3, 3, v4
	v_readlane_b32 s11, v255, 16
	v_ashrrev_i32_e32 v6, 6, v2
	v_and_b32_e32 v3, -16, v3
	s_add_u32 s46, s11, s0
	v_readlane_b32 s0, v255, 15
	v_add_u32_e32 v3, v6, v3
	s_addc_u32 s47, s0, s1
	v_and_b32_e32 v7, 3, v6
	s_mov_b32 s0, 0x3fffe0
	v_lshrrev_b32_e32 v8, 2, v3
	v_lshlrev_b32_e32 v9, 1, v3
	v_and_b32_e32 v2, 0xc0, v2
	v_and_or_b32 v7, v3, s0, v7
	v_and_b32_e32 v8, 4, v8
	v_and_b32_e32 v9, 24, v9
	v_sub_u32_e32 v1, v1, v2
	v_or3_b32 v8, v7, v8, v9
	v_lshlrev_b32_e32 v7, 5, v4
	v_ashrrev_i16_sdwa v1, v233, sext(v1) dst_sel:DWORD dst_unused:UNUSED_PAD src0_sel:DWORD src1_sel:BYTE_0
	v_and_b32_e32 v9, 32, v7
	v_bfe_i32 v7, v1, 0, 16
	v_add_lshl_u32 v1, v9, v7, 1
	v_lshl_add_u32 v150, v8, 10, v1
	v_lshl_add_u32 v152, v3, 10, v1
	v_bfe_i32 v1, v5, 27, 1
	v_lshrrev_b32_e32 v1, 22, v1
	v_add_u32_e32 v1, v0, v1
	v_and_b32_e32 v1, 0xfffffc00, v1
	v_sub_u32_e32 v0, v0, v1
	v_lshrrev_b32_e32 v1, 4, v0
	v_ashrrev_i32_e32 v2, 31, v5
	v_bitop3_b32 v0, v1, v0, 32 bitop3:0x6c
	v_lshrrev_b32_e32 v2, 26, v2
	v_ashrrev_i32_e32 v1, 31, v0
	v_add_u32_e32 v2, v5, v2
	v_lshrrev_b32_e32 v1, 26, v1
	v_ashrrev_i32_e32 v9, 6, v2
	v_add_u32_e32 v1, v0, v1
	v_lshlrev_b32_e32 v2, 3, v9
	v_ashrrev_i32_e32 v8, 6, v1
	v_and_b32_e32 v2, -16, v2
	v_add_u32_e32 v2, v8, v2
	v_and_b32_e32 v3, 3, v8
	v_lshrrev_b32_e32 v10, 2, v2
	v_lshlrev_b32_e32 v11, 1, v2
	v_and_b32_e32 v1, 0xc0, v1
	s_ashr_i32 s11, s10, 6
	v_and_or_b32 v3, v2, s0, v3
	v_and_b32_e32 v10, 4, v10
	v_and_b32_e32 v11, 24, v11
	v_sub_u32_e32 v0, v0, v1
	s_ashr_i32 s14, s10, 8
	s_lshl_b32 s48, s11, 10
	v_or3_b32 v3, v3, v10, v11
	v_lshlrev_b32_e32 v10, 5, v9
	v_ashrrev_i16_sdwa v0, v233, sext(v0) dst_sel:DWORD dst_unused:UNUSED_PAD src0_sel:DWORD src1_sel:BYTE_0
	v_readlane_b32 s0, v254, 13
	v_and_b32_e32 v11, 32, v10
	v_bfe_i32 v10, v0, 0, 16
	v_readlane_b32 s1, v254, 14
	s_add_u32 s22, s46, s0
	v_add_lshl_u32 v0, v11, v10, 1
	s_addc_u32 s23, s47, s1
	s_add_i32 s49, s48, 0
	v_lshl_add_u32 v64, v3, 10, v0
	s_add_i32 m0, s49, 0x10000
	v_lshl_add_u32 v154, v2, 10, v0
	global_load_lds_dwordx4 v64, s[22:23]
	s_add_i32 m0, s49, 0x12000
	s_add_u32 s0, s22, 0x20000
	global_load_lds_dwordx4 v150, s[22:23]
	s_addc_u32 s1, s23, 0
	s_add_i32 m0, s49, 0x14000
	s_add_i32 s50, s49, 0x2000
	global_load_lds_dwordx4 v64, s[0:1]
	s_add_i32 m0, s49, 0x16000
	s_add_i32 s51, s49, 0x4000
	global_load_lds_dwordx4 v150, s[0:1]
	v_readlane_b32 s0, v254, 31
	s_mov_b32 m0, s49
	v_readlane_b32 s1, v254, 32
	s_add_i32 s52, s49, 0x6000
	v_mov_b32_e32 v151, v65
	s_cmp_eq_u32 s14, 1
	v_lshl_add_u64 v[0:1], s[22:23], 0, v[64:65]
	v_lshl_add_u64 v[2:3], s[22:23], 0, v[150:151]
	global_load_lds_dwordx4 v154, s[0:1]
	s_mov_b32 m0, s50
	s_mov_b64 s[24:25], 0x80
	global_load_lds_dwordx4 v152, s[0:1]
	v_readlane_b32 s0, v254, 33
	s_mov_b32 m0, s51
	v_readlane_b32 s1, v254, 34
	s_nop 4
	global_load_lds_dwordx4 v154, s[0:1]
	s_mov_b32 m0, s52
	s_nop 0
	global_load_lds_dwordx4 v152, s[0:1]
	s_cselect_b64 s[0:1], -1, 0
	s_cmp_lg_u32 s14, 1
	s_cbranch_scc1 .LBB0_322
	s_barrier

;     __device__ __forceinline__ void operator()(const f32x4 (&acc)[2][2][4][2], const Unit& u, int wr, int wc, int fr, int fq) const {
;     ...
;             for (int m = 0; m < 4; ++m) rsc[ai][m] = Q ? XS[row0 + ai * HALF + m * 16] * (1.f / (127.f * 127.f)) : 1.f;
; #pragma unroll
;         for (int bj = 0; bj < 2; ++bj)
; #pragma unroll
;             for (int n = 0; n < 2; ++n) cs[bj][n] = Q ? *(const f32x4*)(CS + u.pn * BM + bj * HALF + cw + 4 * n) : (f32x4){1.f, 1.f, 1.f, 1.f};
;     ...
;         for (int a = 0; a < 2; ++a)
; #pragma unroll
;             for (int b = 0; b < 2; ++b)
; #pragma unroll
;                 for (int m = 0; m < 4; ++m)
; #pragma unroll
;                     for (int n = 0; n < 2; ++n) acc[a][b][m][n] = (f32x4){0.f, 0.f, 0.f, 0.f};
;         cur = nxt; cA = nA; cB = nB; ++ui;
.LBB0_327:
	s_ashr_i32 s29, s28, 31
	s_lshl_b64 s[26:27], s[28:29], 18
	v_readlane_b32 s11, v252, 37
	s_add_u32 s30, s11, s26
	v_readlane_b32 s11, v254, 29
	s_addc_u32 s31, s11, s27
	s_and_b64 s[26:27], s[36:37], exec
	s_cselect_b32 s11, s31, s19
	s_cselect_b32 s21, s30, s18
	s_ashr_i32 s25, s24, 31
	s_lshl_b64 s[26:27], s[24:25], 18
	s_add_u32 s34, s46, s26
	s_addc_u32 s35, s47, s27
	s_and_b64 s[26:27], s[36:37], exec
	s_cselect_b32 s25, s35, s23
	s_cselect_b32 s26, s34, s22
	s_add_u32 s18, s18, 0x20080
	s_addc_u32 s19, s19, 0
	s_add_u32 s27, s22, 0x100
	v_mov_b32_e32 v0, 0
	s_addc_u32 s29, s23, 0
	s_mov_b32 s33, -2
	v_mov_b32_e32 v1, v0
	v_mov_b32_e32 v2, v0
	v_mov_b32_e32 v3, v0
	v_mov_b32_e32 v4, v0
	v_mov_b32_e32 v5, v0
	v_mov_b32_e32 v6, v0
	v_mov_b32_e32 v7, v0
	v_mov_b32_e32 v16, v0
	v_mov_b32_e32 v17, v0
	v_mov_b32_e32 v18, v0
	v_mov_b32_e32 v19, v0
	v_mov_b32_e32 v20, v0
	v_mov_b32_e32 v21, v0
	v_mov_b32_e32 v22, v0
	v_mov_b32_e32 v23, v0
	v_mov_b32_e32 v32, v0
	v_mov_b32_e32 v33, v0
	v_mov_b32_e32 v34, v0
	v_mov_b32_e32 v35, v0
	v_mov_b32_e32 v36, v0
	v_mov_b32_e32 v37, v0
	v_mov_b32_e32 v38, v0
	v_mov_b32_e32 v39, v0
	v_mov_b32_e32 v52, v0
	v_mov_b32_e32 v53, v0
	v_mov_b32_e32 v54, v0
	v_mov_b32_e32 v55, v0
	v_mov_b32_e32 v60, v0
	v_mov_b32_e32 v61, v0
	v_mov_b32_e32 v62, v0
	v_mov_b32_e32 v63, v0
	v_mov_b32_e32 v8, v0
	v_mov_b32_e32 v9, v0
	v_mov_b32_e32 v10, v0
	v_mov_b32_e32 v11, v0
	v_mov_b32_e32 v12, v0
	v_mov_b32_e32 v13, v0
	v_mov_b32_e32 v14, v0
	v_mov_b32_e32 v15, v0
	v_mov_b32_e32 v24, v0
	v_mov_b32_e32 v25, v0
	v_mov_b32_e32 v26, v0
	v_mov_b32_e32 v27, v0
	v_mov_b32_e32 v28, v0
	v_mov_b32_e32 v29, v0
	v_mov_b32_e32 v30, v0
	v_mov_b32_e32 v31, v0
	v_mov_b32_e32 v40, v0
	v_mov_b32_e32 v41, v0
	v_mov_b32_e32 v42, v0
	v_mov_b32_e32 v43, v0
	v_mov_b32_e32 v48, v0
	v_mov_b32_e32 v49, v0
	v_mov_b32_e32 v50, v0
	v_mov_b32_e32 v51, v0
	v_mov_b32_e32 v74, v0
	v_mov_b32_e32 v75, v0
	v_mov_b32_e32 v76, v0
	v_mov_b32_e32 v77, v0
	v_mov_b32_e32 v78, v0
	v_mov_b32_e32 v79, v0
	v_mov_b32_e32 v80, v0
	v_mov_b32_e32 v81, v0
	v_mov_b32_e32 v82, v0
	v_mov_b32_e32 v83, v0
	v_mov_b32_e32 v84, v0
	v_mov_b32_e32 v85, v0
	v_mov_b32_e32 v86, v0
	v_mov_b32_e32 v87, v0
	v_mov_b32_e32 v88, v0
	v_mov_b32_e32 v89, v0
	v_mov_b32_e32 v98, v0
	v_mov_b32_e32 v99, v0
	v_mov_b32_e32 v100, v0
	v_mov_b32_e32 v101, v0
	v_mov_b32_e32 v102, v0
	v_mov_b32_e32 v103, v0
	v_mov_b32_e32 v104, v0
	v_mov_b32_e32 v105, v0
	v_mov_b32_e32 v114, v0
	v_mov_b32_e32 v115, v0
	v_mov_b32_e32 v116, v0
	v_mov_b32_e32 v117, v0
	v_mov_b32_e32 v118, v0
	v_mov_b32_e32 v119, v0
	v_mov_b32_e32 v120, v0
	v_mov_b32_e32 v121, v0
	v_mov_b32_e32 v130, v0
	v_mov_b32_e32 v131, v0
	v_mov_b32_e32 v132, v0
	v_mov_b32_e32 v133, v0
	v_mov_b32_e32 v134, v0
	v_mov_b32_e32 v135, v0
	v_mov_b32_e32 v136, v0
	v_mov_b32_e32 v137, v0
	v_mov_b32_e32 v90, v0
	v_mov_b32_e32 v91, v0
	v_mov_b32_e32 v92, v0
	v_mov_b32_e32 v93, v0
	v_mov_b32_e32 v94, v0
	v_mov_b32_e32 v95, v0
	v_mov_b32_e32 v96, v0
	v_mov_b32_e32 v97, v0
	v_mov_b32_e32 v106, v0
	v_mov_b32_e32 v107, v0
	v_mov_b32_e32 v108, v0
	v_mov_b32_e32 v109, v0
	v_mov_b32_e32 v110, v0
	v_mov_b32_e32 v111, v0
	v_mov_b32_e32 v112, v0
	v_mov_b32_e32 v113, v0
	v_mov_b32_e32 v122, v0
	v_mov_b32_e32 v123, v0
	v_mov_b32_e32 v124, v0
	v_mov_b32_e32 v125, v0
	v_mov_b32_e32 v126, v0
	v_mov_b32_e32 v127, v0
	v_mov_b32_e32 v128, v0
	v_mov_b32_e32 v129, v0
	v_mov_b32_e32 v138, v0
	v_mov_b32_e32 v139, v0
	v_mov_b32_e32 v140, v0
	v_mov_b32_e32 v141, v0
	v_mov_b32_e32 v142, v0
	v_mov_b32_e32 v143, v0
	v_mov_b32_e32 v144, v0
	v_mov_b32_e32 v145, v0
	s_mov_b64 s[44:45], 0x80
	v_readfirstlane_b32 s98, v232
	s_xor_b32 s101, s101, 1
	s_nop 0
	s_lshr_b32 s98, s98, 6
	s_cmp_gt_u32 s98, 1
	s_cbranch_scc1 .Lp1_nodma
	s_lshl_b32 s99, s101, 11
	s_add_i32 s99, s99, 0x20400
	v_and_b32_e32 v242, 63, v232
	v_mov_b32_e32 v243, 0
	v_lshlrev_b32_e32 v242, 4, v242
	s_cmp_eq_u32 s98, 1
	s_cbranch_scc1 .Lp1_dma_cs
	v_readlane_b32 s98, v252, 38
	v_readlane_b32 s100, v252, 39
	s_nop 1
	v_mov_b32_e32 v238, s98
	v_mov_b32_e32 v239, s100
	s_lshl_b32 s98, s10, 10
	v_add_u32_e32 v242, s98, v242
	v_lshl_add_u64 v[238:239], v[238:239], 0, v[242:243]
	s_mov_b32 m0, s99
	s_nop 0
	global_load_lds_dwordx4 v[238:239], off
	s_branch .Lp1_nodma
.Lp1_dma_cs:
	v_mov_b32_e32 v238, s20
	v_mov_b32_e32 v239, s55
	s_lshl_b32 s98, s61, 10
	v_add_u32_e32 v242, s98, v242
	v_lshl_add_u64 v[238:239], v[238:239], 0, v[242:243]
	s_add_i32 s99, s99, 0x400
	s_mov_b32 m0, s99
	s_nop 0
	global_load_lds_dwordx4 v[238:239], off
; #define PG8_STAGE(bufoff, gbase, voff) do { _Pragma("unroll") for (int _i = 0; _i < 2; ++_i) \
;         __builtin_amdgcn_global_load_lds((const unsigned*)((const char*)(gbase) + (voff)[_i]), (PG8_LAS unsigned*)(lds + (bufoff) + ldsw + _i * 8192), 16, 0, 0); } while (0)
; #define PG8_LDA(dst, b, h) do { _Pragma("unroll") for (int m = 0; m < 4; ++m) _Pragma("unroll") for (int k = 0; k < 2; ++k) dst[m][k] = *(const PG8_LAS bf16x8*)(lds + PG8_SA(b, h) + aoff + m * 2048 + k * 1024); } while (0)
; #define PG8_LDB(dst, b, h) do { _Pragma("unroll") for (int n = 0; n < 2; ++n) _Pragma("unroll") for (int k = 0; k < 2; ++k) dst[n][k] = *(const PG8_LAS bf16x8*)(lds + PG8_SB(b, h) + boff + n * 2048 + k * 1024); } while (0)
; #define PG8_WAIT_V(n) asm volatile("s_waitcnt vmcnt(" #n ")" ::: "memory")
; #define PG8_WAIT_L(n) asm volatile("s_waitcnt lgkmcnt(" #n ")" ::: "memory")
; #define PG8_BAR __builtin_amdgcn_s_barrier()
; #define PG8_SCHED __builtin_amdgcn_sched_barrier(0)
;     ...
;             PG8_LDB(B0, 0, 0); PG8_LDB(B1, 0, 1); PG8_SCHED; PG8_LDA(At, 0, 0); PG8_STAGE(PG8_SA(1, 1), a1 + hstepA, voffA);
;             PG8_WAIT_V(8); PG8_WAIT_L(0); PG8_BAR; PG8_MMA(0, 0, At, B0); PG8_MMA(0, 1, At, B1); PG8_BAR; PG8_SCHED;
;             PG8_LDA(At, 0, 1); PG8_STAGE(PG8_SB(0, 0), b2, voffB); PG8_STAGE(PG8_SB(0, 1), b2 + hstepB, voffB); PG8_STAGE(PG8_SA(0, 0), a2, voffA);
;             PG8_WAIT_V(8); PG8_WAIT_L(0); PG8_BAR; PG8_MMA(1, 0, At, B0); PG8_MMA(1, 1, At, B1); PG8_BAR; PG8_SCHED;
.Lp1_nodma:
.LBB0_328:
	s_add_u32 s22, s18, 0xfffe0080
	s_addc_u32 s23, s19, -1
	s_add_i32 s40, 0, 0x10000
	s_cmp_eq_u32 s33, 4
	s_cselect_b32 s39, s11, s23
	s_cselect_b32 s38, s21, s22
	s_cselect_b32 s23, s25, s29
	s_cselect_b32 s22, s26, s27
	s_add_i32 s42, 0, 0x14000
	v_add_u32_e32 v70, s40, v215
	v_add_u32_e32 v168, s42, v215
	ds_read_b128 v[44:47], v70
	ds_read_b128 v[56:59], v70 offset:1024
	ds_read_b128 v[66:69], v70 offset:2048
	ds_read_b128 v[70:73], v70 offset:3072
	s_waitcnt lgkmcnt(0)
	ds_read_b128 v[146:149], v168
	ds_read_b128 v[160:163], v168 offset:1024
	ds_read_b128 v[164:167], v168 offset:2048
	ds_read_b128 v[168:171], v168 offset:3072
	v_lshl_add_u64 v[222:223], s[18:19], 0, v[156:157]
	s_add_i32 m0, s49, 0xc000
	ds_read_b128 v[172:175], v216
	ds_read_b128 v[176:179], v216 offset:1024
	ds_read_b128 v[180:183], v216 offset:2048
	ds_read_b128 v[184:187], v216 offset:3072
	ds_read_b128 v[188:191], v216 offset:4096
	ds_read_b128 v[206:209], v216 offset:5120
	ds_read_b128 v[210:213], v216 offset:6144
	ds_read_b128 v[218:221], v216 offset:7168
	global_load_lds_dwordx4 v[222:223], off
	v_lshl_add_u64 v[222:223], s[18:19], 0, v[158:159]
	s_add_i32 m0, s49, 0xe000
	s_nop 0
	global_load_lds_dwordx4 v[222:223], off
	s_waitcnt vmcnt(8)
	s_waitcnt lgkmcnt(0)
	s_barrier
	s_setprio 1
	s_waitcnt lgkmcnt(0)
	v_mfma_i32_16x16x64_i8 v[142:145], v[44:47], v[172:175], v[142:145]
	v_mfma_i32_16x16x64_i8 v[138:141], v[66:69], v[172:175], v[138:141]
	v_mfma_i32_16x16x64_i8 v[126:129], v[44:47], v[180:183], v[126:129]
	v_mfma_i32_16x16x64_i8 v[122:125], v[66:69], v[180:183], v[122:125]
	v_mfma_i32_16x16x64_i8 v[110:113], v[44:47], v[188:191], v[110:113]
	v_mfma_i32_16x16x64_i8 v[106:109], v[66:69], v[188:191], v[106:109]
	v_mfma_i32_16x16x64_i8 v[94:97], v[44:47], v[210:213], v[94:97]
	v_mfma_i32_16x16x64_i8 v[90:93], v[66:69], v[210:213], v[90:93]
	v_mfma_i32_16x16x64_i8 v[142:145], v[56:59], v[176:179], v[142:145]
	v_mfma_i32_16x16x64_i8 v[138:141], v[70:73], v[176:179], v[138:141]
	v_mfma_i32_16x16x64_i8 v[126:129], v[56:59], v[184:187], v[126:129]
	v_mfma_i32_16x16x64_i8 v[122:125], v[70:73], v[184:187], v[122:125]
	v_mfma_i32_16x16x64_i8 v[110:113], v[56:59], v[206:209], v[110:113]
	v_mfma_i32_16x16x64_i8 v[106:109], v[70:73], v[206:209], v[106:109]
	v_mfma_i32_16x16x64_i8 v[94:97], v[56:59], v[218:221], v[94:97]
	v_mfma_i32_16x16x64_i8 v[90:93], v[70:73], v[218:221], v[90:93]
	v_mfma_i32_16x16x64_i8 v[134:137], v[146:149], v[172:175], v[134:137]
	v_mfma_i32_16x16x64_i8 v[130:133], v[164:167], v[172:175], v[130:133]
	v_mfma_i32_16x16x64_i8 v[118:121], v[146:149], v[180:183], v[118:121]
	v_mfma_i32_16x16x64_i8 v[114:117], v[164:167], v[180:183], v[114:117]
	v_mfma_i32_16x16x64_i8 v[102:105], v[146:149], v[188:191], v[102:105]
	v_mfma_i32_16x16x64_i8 v[98:101], v[164:167], v[188:191], v[98:101]
	v_mfma_i32_16x16x64_i8 v[86:89], v[146:149], v[210:213], v[86:89]
	v_mfma_i32_16x16x64_i8 v[82:85], v[164:167], v[210:213], v[82:85]
	v_mfma_i32_16x16x64_i8 v[134:137], v[160:163], v[176:179], v[134:137]
	v_mfma_i32_16x16x64_i8 v[130:133], v[168:171], v[176:179], v[130:133]
	v_mfma_i32_16x16x64_i8 v[118:121], v[160:163], v[184:187], v[118:121]
	v_mfma_i32_16x16x64_i8 v[114:117], v[168:171], v[184:187], v[114:117]
	v_mfma_i32_16x16x64_i8 v[102:105], v[160:163], v[206:209], v[102:105]
	v_mfma_i32_16x16x64_i8 v[98:101], v[168:171], v[206:209], v[98:101]
	v_mfma_i32_16x16x64_i8 v[86:89], v[160:163], v[218:221], v[86:89]
	v_mfma_i32_16x16x64_i8 v[82:85], v[168:171], v[218:221], v[82:85]
	s_setprio 0
	s_barrier
	s_add_i32 s40, s40, s48
	v_lshl_add_u64 v[222:223], s[22:23], 0, v[64:65]
	s_mov_b32 m0, s40
	ds_read_b128 v[172:175], v216 offset:16384
	ds_read_b128 v[176:179], v216 offset:17408
	ds_read_b128 v[180:183], v216 offset:18432
	ds_read_b128 v[184:187], v216 offset:19456
	ds_read_b128 v[188:191], v216 offset:20480
	ds_read_b128 v[206:209], v216 offset:21504
	ds_read_b128 v[210:213], v216 offset:22528
	ds_read_b128 v[218:221], v216 offset:23552
	global_load_lds_dwordx4 v[222:223], off
	s_add_i32 m0, s40, 0x2000
	s_add_u32 s40, s22, 0x20000
	v_lshl_add_u64 v[224:225], s[22:23], 0, v[150:151]
	s_addc_u32 s41, s23, 0
	s_add_i32 s42, s42, s48
	global_load_lds_dwordx4 v[224:225], off
	v_lshl_add_u64 v[226:227], s[40:41], 0, v[64:65]
	s_mov_b32 m0, s42
	v_lshl_add_u64 v[228:229], s[38:39], 0, v[152:153]
	global_load_lds_dwordx4 v[226:227], off
	v_lshl_add_u64 v[226:227], s[40:41], 0, v[150:151]
	s_add_i32 m0, s42, 0x2000
	s_nop 0
	global_load_lds_dwordx4 v[226:227], off
	v_lshl_add_u64 v[226:227], s[38:39], 0, v[154:155]
	s_mov_b32 m0, s49
	s_nop 0
	global_load_lds_dwordx4 v[226:227], off
	s_mov_b32 m0, s50
	s_nop 0
	global_load_lds_dwordx4 v[228:229], off
	s_waitcnt vmcnt(8)
	s_waitcnt lgkmcnt(0)
	s_barrier
; #define PG8_STAGE(bufoff, gbase, voff) do { _Pragma("unroll") for (int _i = 0; _i < 2; ++_i) \
;         __builtin_amdgcn_global_load_lds((const unsigned*)((const char*)(gbase) + (voff)[_i]), (PG8_LAS unsigned*)(lds + (bufoff) + ldsw + _i * 8192), 16, 0, 0); } while (0)
; #define PG8_LDA(dst, b, h) do { _Pragma("unroll") for (int m = 0; m < 4; ++m) _Pragma("unroll") for (int k = 0; k < 2; ++k) dst[m][k] = *(const PG8_LAS bf16x8*)(lds + PG8_SA(b, h) + aoff + m * 2048 + k * 1024); } while (0)
; #define PG8_LDB(dst, b, h) do { _Pragma("unroll") for (int n = 0; n < 2; ++n) _Pragma("unroll") for (int k = 0; k < 2; ++k) dst[n][k] = *(const PG8_LAS bf16x8*)(lds + PG8_SB(b, h) + boff + n * 2048 + k * 1024); } while (0)
; #define PG8_WAIT_V(n) asm volatile("s_waitcnt vmcnt(" #n ")" ::: "memory")
; #define PG8_WAIT_L(n) asm volatile("s_waitcnt lgkmcnt(" #n ")" ::: "memory")
; #define PG8_BAR __builtin_amdgcn_s_barrier()
; #define PG8_SCHED __builtin_amdgcn_sched_barrier(0)
;     ...
;             PG8_WAIT_V(8); PG8_WAIT_L(0); PG8_BAR; PG8_MMA(1, 0, At, B0); PG8_MMA(1, 1, At, B1); PG8_BAR; PG8_SCHED;
;             PG8_LDB(B0, 1, 0); PG8_LDB(B1, 1, 1); PG8_SCHED; PG8_LDA(At, 1, 0); PG8_STAGE(PG8_SA(0, 1), a2 + hstepA, voffA);
;             PG8_WAIT_V(8); PG8_WAIT_L(0); PG8_BAR; PG8_MMA(0, 0, At, B0); PG8_MMA(0, 1, At, B1); PG8_BAR; PG8_SCHED;
	s_setprio 1
	s_waitcnt lgkmcnt(0)
	v_mfma_i32_16x16x64_i8 v[78:81], v[44:47], v[172:175], v[78:81]
	v_mfma_i32_16x16x64_i8 v[74:77], v[66:69], v[172:175], v[74:77]
	v_mfma_i32_16x16x64_i8 v[48:51], v[44:47], v[180:183], v[48:51]
	v_mfma_i32_16x16x64_i8 v[40:43], v[66:69], v[180:183], v[40:43]
	v_mfma_i32_16x16x64_i8 v[28:31], v[44:47], v[188:191], v[28:31]
	v_mfma_i32_16x16x64_i8 v[24:27], v[66:69], v[188:191], v[24:27]
	v_mfma_i32_16x16x64_i8 v[12:15], v[44:47], v[210:213], v[12:15]
	v_mfma_i32_16x16x64_i8 v[8:11], v[66:69], v[210:213], v[8:11]
	v_mfma_i32_16x16x64_i8 v[78:81], v[56:59], v[176:179], v[78:81]
	v_mfma_i32_16x16x64_i8 v[74:77], v[70:73], v[176:179], v[74:77]
	v_mfma_i32_16x16x64_i8 v[48:51], v[56:59], v[184:187], v[48:51]
	v_mfma_i32_16x16x64_i8 v[40:43], v[70:73], v[184:187], v[40:43]
	v_mfma_i32_16x16x64_i8 v[28:31], v[56:59], v[206:209], v[28:31]
	v_mfma_i32_16x16x64_i8 v[24:27], v[70:73], v[206:209], v[24:27]
	v_mfma_i32_16x16x64_i8 v[12:15], v[56:59], v[218:221], v[12:15]
	v_mfma_i32_16x16x64_i8 v[8:11], v[70:73], v[218:221], v[8:11]
	v_mfma_i32_16x16x64_i8 v[52:55], v[164:167], v[172:175], v[52:55]
	v_mfma_i32_16x16x64_i8 v[36:39], v[146:149], v[180:183], v[36:39]
	v_mfma_i32_16x16x64_i8 v[32:35], v[164:167], v[180:183], v[32:35]
	v_mfma_i32_16x16x64_i8 v[20:23], v[146:149], v[188:191], v[20:23]
	v_mfma_i32_16x16x64_i8 v[16:19], v[164:167], v[188:191], v[16:19]
	v_mfma_i32_16x16x64_i8 v[4:7], v[146:149], v[210:213], v[4:7]
	v_mfma_i32_16x16x64_i8 v[0:3], v[164:167], v[210:213], v[0:3]
	v_mfma_i32_16x16x64_i8 v[44:47], v[146:149], v[172:175], v[60:63]
	v_mfma_i32_16x16x64_i8 v[52:55], v[168:171], v[176:179], v[52:55]
	v_mfma_i32_16x16x64_i8 v[36:39], v[160:163], v[184:187], v[36:39]
	v_mfma_i32_16x16x64_i8 v[32:35], v[168:171], v[184:187], v[32:35]
	v_mfma_i32_16x16x64_i8 v[20:23], v[160:163], v[206:209], v[20:23]
	v_mfma_i32_16x16x64_i8 v[16:19], v[168:171], v[206:209], v[16:19]
	v_mfma_i32_16x16x64_i8 v[4:7], v[160:163], v[218:221], v[4:7]
	v_mfma_i32_16x16x64_i8 v[0:3], v[168:171], v[218:221], v[0:3]
	v_mfma_i32_16x16x64_i8 v[44:47], v[160:163], v[176:179], v[44:47]
	s_setprio 0
	s_barrier
	s_add_i32 s40, 0, 0x18000
	s_add_i32 s41, 0, 0x1c000
	v_add_u32_e32 v70, s40, v215
	v_add_u32_e32 v168, s41, v215
	ds_read_b128 v[56:59], v70
	ds_read_b128 v[60:63], v70 offset:1024
	ds_read_b128 v[66:69], v70 offset:2048
	ds_read_b128 v[70:73], v70 offset:3072
	ds_read_b128 v[146:149], v168
	ds_read_b128 v[160:163], v168 offset:1024
	ds_read_b128 v[164:167], v168 offset:2048
	ds_read_b128 v[168:171], v168 offset:3072
	s_add_u32 s38, s38, 0x20000
	s_addc_u32 s39, s39, 0
	s_mov_b32 m0, s51
	v_lshl_add_u64 v[230:231], s[38:39], 0, v[154:155]
	ds_read_b128 v[172:175], v216 offset:32768
	ds_read_b128 v[176:179], v216 offset:33792
	ds_read_b128 v[180:183], v216 offset:34816
	ds_read_b128 v[184:187], v216 offset:35840
	ds_read_b128 v[188:191], v216 offset:36864
	ds_read_b128 v[206:209], v216 offset:37888
	ds_read_b128 v[210:213], v216 offset:38912
	ds_read_b128 v[218:221], v216 offset:39936
	global_load_lds_dwordx4 v[230:231], off
	v_lshl_add_u64 v[230:231], s[38:39], 0, v[152:153]
	s_mov_b32 m0, s52
	s_nop 0
	global_load_lds_dwordx4 v[230:231], off
	s_waitcnt vmcnt(8)
	s_waitcnt lgkmcnt(0)
	s_barrier
	s_setprio 1
	s_waitcnt lgkmcnt(0)
	v_mfma_i32_16x16x64_i8 v[142:145], v[56:59], v[172:175], v[142:145]
	v_mfma_i32_16x16x64_i8 v[138:141], v[66:69], v[172:175], v[138:141]
	v_mfma_i32_16x16x64_i8 v[126:129], v[56:59], v[180:183], v[126:129]
	v_mfma_i32_16x16x64_i8 v[122:125], v[66:69], v[180:183], v[122:125]
	v_mfma_i32_16x16x64_i8 v[110:113], v[56:59], v[188:191], v[110:113]
	v_mfma_i32_16x16x64_i8 v[106:109], v[66:69], v[188:191], v[106:109]
	v_mfma_i32_16x16x64_i8 v[94:97], v[56:59], v[210:213], v[94:97]
	v_mfma_i32_16x16x64_i8 v[90:93], v[66:69], v[210:213], v[90:93]
	v_mfma_i32_16x16x64_i8 v[142:145], v[60:63], v[176:179], v[142:145]
	v_mfma_i32_16x16x64_i8 v[138:141], v[70:73], v[176:179], v[138:141]
	v_mfma_i32_16x16x64_i8 v[126:129], v[60:63], v[184:187], v[126:129]
	v_mfma_i32_16x16x64_i8 v[122:125], v[70:73], v[184:187], v[122:125]
	v_mfma_i32_16x16x64_i8 v[110:113], v[60:63], v[206:209], v[110:113]
	v_mfma_i32_16x16x64_i8 v[106:109], v[70:73], v[206:209], v[106:109]
	v_mfma_i32_16x16x64_i8 v[94:97], v[60:63], v[218:221], v[94:97]
	v_mfma_i32_16x16x64_i8 v[90:93], v[70:73], v[218:221], v[90:93]
	v_mfma_i32_16x16x64_i8 v[134:137], v[146:149], v[172:175], v[134:137]
	v_mfma_i32_16x16x64_i8 v[130:133], v[164:167], v[172:175], v[130:133]
	v_mfma_i32_16x16x64_i8 v[118:121], v[146:149], v[180:183], v[118:121]
	v_mfma_i32_16x16x64_i8 v[114:117], v[164:167], v[180:183], v[114:117]
	v_mfma_i32_16x16x64_i8 v[102:105], v[146:149], v[188:191], v[102:105]
	v_mfma_i32_16x16x64_i8 v[98:101], v[164:167], v[188:191], v[98:101]
	v_mfma_i32_16x16x64_i8 v[86:89], v[146:149], v[210:213], v[86:89]
	v_mfma_i32_16x16x64_i8 v[82:85], v[164:167], v[210:213], v[82:85]
	v_mfma_i32_16x16x64_i8 v[134:137], v[160:163], v[176:179], v[134:137]
	v_mfma_i32_16x16x64_i8 v[130:133], v[168:171], v[176:179], v[130:133]
	v_mfma_i32_16x16x64_i8 v[118:121], v[160:163], v[184:187], v[118:121]
	v_mfma_i32_16x16x64_i8 v[114:117], v[168:171], v[184:187], v[114:117]
	v_mfma_i32_16x16x64_i8 v[102:105], v[160:163], v[206:209], v[102:105]
	v_mfma_i32_16x16x64_i8 v[98:101], v[168:171], v[206:209], v[98:101]
	v_mfma_i32_16x16x64_i8 v[86:89], v[160:163], v[218:221], v[86:89]
	v_mfma_i32_16x16x64_i8 v[82:85], v[168:171], v[218:221], v[82:85]
	s_setprio 0
	s_barrier
; #define PG8_STAGE(bufoff, gbase, voff) do { _Pragma("unroll") for (int _i = 0; _i < 2; ++_i) \
;         __builtin_amdgcn_global_load_lds((const unsigned*)((const char*)(gbase) + (voff)[_i]), (PG8_LAS unsigned*)(lds + (bufoff) + ldsw + _i * 8192), 16, 0, 0); } while (0)
; #define PG8_LDA(dst, b, h) do { _Pragma("unroll") for (int m = 0; m < 4; ++m) _Pragma("unroll") for (int k = 0; k < 2; ++k) dst[m][k] = *(const PG8_LAS bf16x8*)(lds + PG8_SA(b, h) + aoff + m * 2048 + k * 1024); } while (0)
; #define PG8_WAIT_V(n) asm volatile("s_waitcnt vmcnt(" #n ")" ::: "memory")
; #define PG8_WAIT_L(n) asm volatile("s_waitcnt lgkmcnt(" #n ")" ::: "memory")
; #define PG8_BAR __builtin_amdgcn_s_barrier()
; #define PG8_SCHED __builtin_amdgcn_sched_barrier(0)
;     __device__ __forceinline__ void operator()(const f32x4 (&acc)[2][2][4][2], const Unit& u, int wr, int wc, int fr, int fq) const {
;     ...
;             for (int m = 0; m < 4; ++m) rsc[ai][m] = Q ? XS[row0 + ai * HALF + m * 16] * (1.f / (127.f * 127.f)) : 1.f;
; #pragma unroll
;         for (int bj = 0; bj < 2; ++bj)
; #pragma unroll
;             for (int n = 0; n < 2; ++n) cs[bj][n] = Q ? *(const f32x4*)(CS + u.pn * BM + bj * HALF + cw + 4 * n) : (f32x4){1.f, 1.f, 1.f, 1.f};
;     ...
;             PG8_LDA(At, 1, 1); PG8_STAGE(PG8_SB(1, 0), b3, voffB); PG8_STAGE(PG8_SB(1, 1), b3 + hstepB, voffB); PG8_STAGE(PG8_SA(1, 0), a3, voffA);
;             PG8_WAIT_V(8); PG8_WAIT_L(0); PG8_BAR; PG8_MMA(1, 0, At, B0); PG8_MMA(1, 1, At, B1); PG8_BAR; PG8_SCHED;
	s_add_i32 s38, s40, s48
	v_lshl_add_u64 v[222:223], v[222:223], 0, s[44:45]
	s_mov_b32 m0, s38
	ds_read_b128 v[172:175], v216 offset:49152
	ds_read_b128 v[176:179], v216 offset:50176
	ds_read_b128 v[180:183], v216 offset:51200
	ds_read_b128 v[184:187], v216 offset:52224
	ds_read_b128 v[188:191], v216 offset:53248
	ds_read_b128 v[206:209], v216 offset:54272
	ds_read_b128 v[210:213], v216 offset:55296
	ds_read_b128 v[218:221], v216 offset:56320
	global_load_lds_dwordx4 v[222:223], off
	s_add_i32 m0, s38, 0x2000
	s_add_u32 s22, s22, 0x20080
	v_lshl_add_u64 v[222:223], v[224:225], 0, s[44:45]
	s_addc_u32 s23, s23, 0
	s_add_i32 s38, s41, s48
	global_load_lds_dwordx4 v[222:223], off
	v_lshl_add_u64 v[222:223], s[22:23], 0, v[64:65]
	s_mov_b32 m0, s38
	s_nop 0
	global_load_lds_dwordx4 v[222:223], off
	v_lshl_add_u64 v[222:223], s[22:23], 0, v[150:151]
	s_add_i32 m0, s38, 0x2000
	s_nop 0
	global_load_lds_dwordx4 v[222:223], off
	v_lshl_add_u64 v[222:223], v[226:227], 0, s[44:45]
	s_mov_b32 m0, s58
	s_nop 0
	global_load_lds_dwordx4 v[222:223], off
	v_lshl_add_u64 v[222:223], v[228:229], 0, s[44:45]
	s_mov_b32 m0, s59
	s_nop 0
	global_load_lds_dwordx4 v[222:223], off
	s_waitcnt vmcnt(8)
	s_waitcnt lgkmcnt(0)
	s_barrier
	s_setprio 1
	s_waitcnt lgkmcnt(0)
	v_mfma_i32_16x16x64_i8 v[78:81], v[56:59], v[172:175], v[78:81]
	v_mfma_i32_16x16x64_i8 v[74:77], v[66:69], v[172:175], v[74:77]
	v_mfma_i32_16x16x64_i8 v[48:51], v[56:59], v[180:183], v[48:51]
	v_mfma_i32_16x16x64_i8 v[40:43], v[66:69], v[180:183], v[40:43]
	v_mfma_i32_16x16x64_i8 v[28:31], v[56:59], v[188:191], v[28:31]
	v_mfma_i32_16x16x64_i8 v[24:27], v[66:69], v[188:191], v[24:27]
	v_mfma_i32_16x16x64_i8 v[12:15], v[56:59], v[210:213], v[12:15]
	v_mfma_i32_16x16x64_i8 v[8:11], v[66:69], v[210:213], v[8:11]
	v_mfma_i32_16x16x64_i8 v[78:81], v[60:63], v[176:179], v[78:81]
	v_mfma_i32_16x16x64_i8 v[74:77], v[70:73], v[176:179], v[74:77]
	v_mfma_i32_16x16x64_i8 v[48:51], v[60:63], v[184:187], v[48:51]
	v_mfma_i32_16x16x64_i8 v[40:43], v[70:73], v[184:187], v[40:43]
	v_mfma_i32_16x16x64_i8 v[28:31], v[60:63], v[206:209], v[28:31]
	v_mfma_i32_16x16x64_i8 v[24:27], v[70:73], v[206:209], v[24:27]
	v_mfma_i32_16x16x64_i8 v[12:15], v[60:63], v[218:221], v[12:15]
	v_mfma_i32_16x16x64_i8 v[8:11], v[70:73], v[218:221], v[8:11]
	v_mfma_i32_16x16x64_i8 v[44:47], v[146:149], v[172:175], v[44:47]
	v_mfma_i32_16x16x64_i8 v[60:63], v[160:163], v[176:179], v[44:47]
	v_mfma_i32_16x16x64_i8 v[44:47], v[164:167], v[172:175], v[52:55]
	v_mfma_i32_16x16x64_i8 v[36:39], v[146:149], v[180:183], v[36:39]
	v_mfma_i32_16x16x64_i8 v[32:35], v[164:167], v[180:183], v[32:35]
	v_mfma_i32_16x16x64_i8 v[20:23], v[146:149], v[188:191], v[20:23]
	v_mfma_i32_16x16x64_i8 v[16:19], v[164:167], v[188:191], v[16:19]
	v_mfma_i32_16x16x64_i8 v[4:7], v[146:149], v[210:213], v[4:7]
	v_mfma_i32_16x16x64_i8 v[0:3], v[164:167], v[210:213], v[0:3]
	v_mfma_i32_16x16x64_i8 v[52:55], v[168:171], v[176:179], v[44:47]
	v_mfma_i32_16x16x64_i8 v[36:39], v[160:163], v[184:187], v[36:39]
	v_mfma_i32_16x16x64_i8 v[32:35], v[168:171], v[184:187], v[32:35]
	v_mfma_i32_16x16x64_i8 v[20:23], v[160:163], v[206:209], v[20:23]
	v_mfma_i32_16x16x64_i8 v[16:19], v[168:171], v[206:209], v[16:19]
	v_mfma_i32_16x16x64_i8 v[4:7], v[160:163], v[218:221], v[4:7]
	v_mfma_i32_16x16x64_i8 v[0:3], v[168:171], v[218:221], v[0:3]
	s_setprio 0
	s_barrier
	s_add_i32 s33, s33, 2
	s_add_u32 s18, s18, 0x100
	s_addc_u32 s19, s19, 0
	s_add_u32 s27, s27, 0x100
	s_addc_u32 s29, s29, 0
	s_cmp_gt_u32 s33, 5
	s_cbranch_scc0 .LBB0_328
	s_and_b64 vcc, exec, s[12:13]
	s_cbranch_vccz .LBB0_331
	s_barrier
.LBB0_331:
	s_lshl_b32 s10, s10, 8
	v_mov_b32_e32 v44, v196
	v_mov_b32_e32 v163, v214
	s_add_i32 s10, s10, s56
	s_lshl_b32 s38, s61, 8
	v_add_u32_e32 v188, s10, v44
	v_readlane_b32 s10, v252, 38
	v_ashrrev_i32_e32 v189, 31, v188
	v_readlane_b32 s11, v252, 39
	s_ashr_i32 s39, s38, 31
	v_lshl_add_u32 v206, v163, 3, s57
	v_lshl_add_u64 v[44:45], v[188:189], 2, s[10:11]
	s_lshl_b64 s[10:11], s[38:39], 2
	s_add_u32 s10, s20, s10
	s_addc_u32 s11, s55, s11
	v_ashrrev_i32_e32 v207, 31, v206
	v_lshl_add_u64 v[56:57], v[206:207], 2, s[10:11]
	v_add_u32_e32 v237, s56, v196
	s_lshl_b32 s98, s101, 11
	s_add_i32 s98, s98, 0x20400
	v_lshl_add_u32 v238, v214, 3, s57
	s_add_i32 s99, s98, 0x400
	v_lshl_add_u32 v237, v237, 2, s98
	v_lshl_add_u32 v238, v238, 2, s99
	ds_read_b32 v146, v237
	ds_read_b32 v147, v237 offset:64
	ds_read_b32 v148, v237 offset:128
	ds_read_b32 v149, v237 offset:192
	ds_read_b32 v162, v237 offset:512
	ds_read_b32 v166, v237 offset:576
	ds_read_b32 v167, v237 offset:640
	ds_read_b32 v171, v237 offset:704
	ds_read_b128 v[66:69], v238 offset:16
	ds_read_b128 v[70:73], v238
	s_nop 0
	ds_read_b128 v[44:47], v238 offset:528
	s_nop 0
	ds_read_b128 v[56:59], v238 offset:512
	v_add_u32_e32 v184, 16, v188
	v_add_u32_e32 v180, 32, v188
	v_add_u32_e32 v176, 48, v188
	v_add_u32_e32 v172, 0x80, v188
	v_add_u32_e32 v168, 0x90, v188
	v_add_u32_e32 v164, 0xa0, v188
	v_add_u32_e32 v160, 0xb0, v188
	v_ashrrev_i32_e32 v185, 31, v184
	v_ashrrev_i32_e32 v181, 31, v180
	v_ashrrev_i32_e32 v177, 31, v176
	v_ashrrev_i32_e32 v173, 31, v172
	v_ashrrev_i32_e32 v169, 31, v168
	v_ashrrev_i32_e32 v165, 31, v164
	v_ashrrev_i32_e32 v161, 31, v160
	s_cmp_gt_i32 s61, 7
	s_mov_b64 s[18:19], -1
	s_waitcnt lgkmcnt(0)
	v_mul_f32_e32 v190, 0x38820610, v146
	v_mul_f32_e32 v186, 0x38820610, v147
	v_mul_f32_e32 v182, 0x38820610, v148
	v_mul_f32_e32 v178, 0x38820610, v149
	v_mul_f32_e32 v174, 0x38820610, v162
	v_mul_f32_e32 v170, 0x38820610, v166
	v_mul_f32_e32 v166, 0x38820610, v167
	v_mul_f32_e32 v162, 0x38820610, v171
	s_cbranch_scc0 .LBB0_342
	s_add_i32 s10, s61, -8
	s_cmp_lt_u32 s10, 4
	s_cselect_b64 s[40:41], -1, 0
	s_and_b64 vcc, exec, s[40:41]
	s_cbranch_vccnz .LBB0_344
	s_lshr_b32 s10, s10, 2
	s_cmp_lt_i32 s10, 2
	s_cbranch_scc1 .LBB0_340
	s_cmp_lt_i32 s10, 3
	s_mov_b64 s[42:43], s[4:5]
	s_cbranch_scc1 .LBB0_339
	s_cmp_lg_u32 s10, 3
	s_cbranch_scc0 .LBB0_337
	s_mov_b64 s[18:19], 0
